# up-phase SwiGLU epilogue re-scheduled: 8 independent exp/rcp chains per store block, packed f32 multiplies (same f32 ops per value)
# speedup vs baseline: 1.0027x; 1.0027x over previous
.Lmskip_66_6:
	s_barrier
	s_add_u32 s42, s42, 0x40080
	s_addc_u32 s43, s43, 0
	s_mov_b32 m0, s64
	v_lshl_add_u64 v[142:143], s[42:43], 0, v[184:185]
	global_load_lds_dwordx4 v[142:143], off
	v_lshl_add_u64 v[142:143], s[42:43], 0, v[128:129]
	s_mov_b32 m0, s65
	s_nop 0
	global_load_lds_dwordx4 v[142:143], off
	s_add_i32 s96, s96, 2
	s_add_u32 s40, s40, 0x100
	s_addc_u32 s41, s41, 0
	s_add_u32 s26, s26, 0x100
	s_addc_u32 s27, s27, 0
	s_cmp_gt_u32 s96, 13
	s_cbranch_scc0 .LBB0_66
	v_mul_f32_e32 v160, 0xbfb8aa3b, v124
	v_mul_f32_e32 v161, 0xbfb8aa3b, v125
	v_mul_f32_e32 v162, 0xbfb8aa3b, v126
	v_mul_f32_e32 v163, 0xbfb8aa3b, v127
	v_mul_f32_e32 v164, 0xbfb8aa3b, v116
	v_mul_f32_e32 v165, 0xbfb8aa3b, v117
	v_mul_f32_e32 v166, 0xbfb8aa3b, v118
	v_mul_f32_e32 v167, 0xbfb8aa3b, v119
	v_exp_f32_e32 v160, v160
	v_exp_f32_e32 v161, v161
	v_exp_f32_e32 v162, v162
	v_exp_f32_e32 v163, v163
	v_exp_f32_e32 v164, v164
	v_exp_f32_e32 v165, v165
	v_exp_f32_e32 v166, v166
	v_exp_f32_e32 v167, v167
	v_add_f32_e32 v160, 1.0, v160
	v_add_f32_e32 v161, 1.0, v161
	v_add_f32_e32 v162, 1.0, v162
	v_add_f32_e32 v163, 1.0, v163
	v_add_f32_e32 v164, 1.0, v164
	v_add_f32_e32 v165, 1.0, v165
	v_add_f32_e32 v166, 1.0, v166
	v_add_f32_e32 v167, 1.0, v167
	v_rcp_f32_e32 v160, v160
	v_rcp_f32_e32 v161, v161
	v_rcp_f32_e32 v162, v162
	v_rcp_f32_e32 v163, v163
	v_rcp_f32_e32 v164, v164
	v_rcp_f32_e32 v165, v165
	v_rcp_f32_e32 v166, v166
	v_rcp_f32_e32 v167, v167
	v_pk_mul_f32 v[160:161], v[124:125], v[160:161]
	v_pk_mul_f32 v[162:163], v[126:127], v[162:163]
	v_pk_mul_f32 v[164:165], v[116:117], v[164:165]
	v_pk_mul_f32 v[166:167], v[118:119], v[166:167]
	v_pk_mul_f32 v[120:121], v[160:161], v[120:121]
	v_pk_mul_f32 v[122:123], v[162:163], v[122:123]
	v_pk_mul_f32 v[112:113], v[164:165], v[112:113]
	v_pk_mul_f32 v[114:115], v[166:167], v[114:115]
	v_readlane_b32 s4, v254, 2
	v_lshl_or_b32 v144, s71, 7, v141
	v_readlane_b32 s5, v254, 3
	v_lshl_add_u32 v142, s38, 8, v138
	s_cmp_eq_u32 s100, 2
	s_cbranch_scc0 .Luph_noshift
	v_add_u32_e32 v142, 0x80, v142
.Luph_noshift:
	v_ashrrev_i32_e32 v145, 31, v144
	s_and_b64 vcc, exec, s[22:23]
	s_mov_b32 s71, s28
	s_mov_b32 s38, s30
	s_mov_b64 s[42:43], s[36:37]
	s_mov_b64 s[40:41], s[34:35]
	v_readlane_b32 s96, v255, 22
	v_cvt_pk_bf16_f32 v117, v122, v123
	v_cvt_pk_bf16_f32 v118, v112, v113
	v_mov_b64_e32 v[112:113], s[4:5]
	s_movk_i32 s4, 0x1600
	v_cvt_pk_bf16_f32 v116, v120, v121
	v_cvt_pk_bf16_f32 v119, v114, v115
	v_mad_i64_i32 v[120:121], s[26:27], v142, s4, v[112:113]
	v_lshlrev_b64 v[114:115], 1, v[144:145]
	v_lshl_add_u64 v[120:121], v[120:121], 0, v[114:115]
	global_store_dwordx4 v[120:121], v[116:119], off
	s_nop 1
	v_mul_f32_e32 v160, 0xbfb8aa3b, v108
	v_mul_f32_e32 v161, 0xbfb8aa3b, v109
	v_mul_f32_e32 v162, 0xbfb8aa3b, v110
	v_mul_f32_e32 v163, 0xbfb8aa3b, v111
	v_mul_f32_e32 v164, 0xbfb8aa3b, v100
	v_mul_f32_e32 v165, 0xbfb8aa3b, v101
	v_mul_f32_e32 v166, 0xbfb8aa3b, v102
	v_mul_f32_e32 v167, 0xbfb8aa3b, v103
	v_exp_f32_e32 v160, v160
	v_exp_f32_e32 v161, v161
	v_exp_f32_e32 v162, v162
	v_exp_f32_e32 v163, v163
	v_exp_f32_e32 v164, v164
	v_exp_f32_e32 v165, v165
	v_exp_f32_e32 v166, v166
	v_exp_f32_e32 v167, v167
	v_add_f32_e32 v160, 1.0, v160
	v_add_f32_e32 v161, 1.0, v161
	v_add_f32_e32 v162, 1.0, v162
	v_add_f32_e32 v163, 1.0, v163
	v_add_f32_e32 v164, 1.0, v164
	v_add_f32_e32 v165, 1.0, v165
	v_add_f32_e32 v166, 1.0, v166
	v_add_f32_e32 v167, 1.0, v167
	v_rcp_f32_e32 v160, v160
	v_rcp_f32_e32 v161, v161
	v_rcp_f32_e32 v162, v162
	v_rcp_f32_e32 v163, v163
	v_rcp_f32_e32 v164, v164
	v_rcp_f32_e32 v165, v165
	v_rcp_f32_e32 v166, v166
	v_rcp_f32_e32 v167, v167
	v_pk_mul_f32 v[160:161], v[108:109], v[160:161]
	v_pk_mul_f32 v[162:163], v[110:111], v[162:163]
	v_pk_mul_f32 v[164:165], v[100:101], v[164:165]
	v_pk_mul_f32 v[166:167], v[102:103], v[166:167]
	v_pk_mul_f32 v[104:105], v[160:161], v[104:105]
	v_pk_mul_f32 v[106:107], v[162:163], v[106:107]
	v_pk_mul_f32 v[100:101], v[164:165], v[96:97]
	v_mul_f32_e32 v102, v166, v98
	v_mul_f32_e32 v99, v167, v99
	v_cvt_pk_bf16_f32 v97, v106, v107
	v_cvt_pk_bf16_f32 v98, v100, v101
	v_or_b32_e32 v103, 16, v142
	v_mad_i64_i32 v[100:101], s[26:27], v103, s4, v[112:113]
	v_cvt_pk_bf16_f32 v96, v104, v105
	v_lshl_add_u64 v[100:101], v[100:101], 0, v[114:115]
	v_cvt_pk_bf16_f32 v99, v102, v99
	global_store_dwordx4 v[100:101], v[96:99], off
	s_nop 1
	v_mul_f32_e32 v160, 0xbfb8aa3b, v92
	v_mul_f32_e32 v161, 0xbfb8aa3b, v93
	v_mul_f32_e32 v162, 0xbfb8aa3b, v94
	v_mul_f32_e32 v163, 0xbfb8aa3b, v95
	v_mul_f32_e32 v164, 0xbfb8aa3b, v84
	v_mul_f32_e32 v165, 0xbfb8aa3b, v85
	v_mul_f32_e32 v166, 0xbfb8aa3b, v86
	v_mul_f32_e32 v167, 0xbfb8aa3b, v87
	v_exp_f32_e32 v160, v160
	v_exp_f32_e32 v161, v161
	v_exp_f32_e32 v162, v162
	v_exp_f32_e32 v163, v163
	v_exp_f32_e32 v164, v164
	v_exp_f32_e32 v165, v165
	v_exp_f32_e32 v166, v166
	v_exp_f32_e32 v167, v167
	v_add_f32_e32 v160, 1.0, v160
	v_add_f32_e32 v161, 1.0, v161
	v_add_f32_e32 v162, 1.0, v162
	v_add_f32_e32 v163, 1.0, v163
	v_add_f32_e32 v164, 1.0, v164
	v_add_f32_e32 v165, 1.0, v165
	v_add_f32_e32 v166, 1.0, v166
	v_add_f32_e32 v167, 1.0, v167
	v_rcp_f32_e32 v160, v160
	v_rcp_f32_e32 v161, v161
	v_rcp_f32_e32 v162, v162
	v_rcp_f32_e32 v163, v163
	v_rcp_f32_e32 v164, v164
	v_rcp_f32_e32 v165, v165
	v_rcp_f32_e32 v166, v166
	v_rcp_f32_e32 v167, v167
	v_pk_mul_f32 v[160:161], v[92:93], v[160:161]
	v_pk_mul_f32 v[162:163], v[94:95], v[162:163]
	v_pk_mul_f32 v[164:165], v[84:85], v[164:165]
	v_pk_mul_f32 v[166:167], v[86:87], v[166:167]
	v_pk_mul_f32 v[88:89], v[160:161], v[88:89]
	v_pk_mul_f32 v[90:91], v[162:163], v[90:91]
	v_pk_mul_f32 v[84:85], v[164:165], v[80:81]
	v_mul_f32_e32 v86, v166, v82
	v_mul_f32_e32 v83, v167, v83
	v_cvt_pk_bf16_f32 v81, v90, v91
	v_cvt_pk_bf16_f32 v82, v84, v85
	v_or_b32_e32 v87, 32, v142
	v_mad_i64_i32 v[84:85], s[26:27], v87, s4, v[112:113]
	v_cvt_pk_bf16_f32 v80, v88, v89
	v_lshl_add_u64 v[84:85], v[84:85], 0, v[114:115]
	v_cvt_pk_bf16_f32 v83, v86, v83
	global_store_dwordx4 v[84:85], v[80:83], off
	s_nop 1
	v_mul_f32_e32 v160, 0xbfb8aa3b, v76
	v_mul_f32_e32 v161, 0xbfb8aa3b, v77
	v_mul_f32_e32 v162, 0xbfb8aa3b, v78
	v_mul_f32_e32 v163, 0xbfb8aa3b, v79
	v_mul_f32_e32 v164, 0xbfb8aa3b, v68
	v_mul_f32_e32 v165, 0xbfb8aa3b, v69
	v_mul_f32_e32 v166, 0xbfb8aa3b, v70
	v_mul_f32_e32 v167, 0xbfb8aa3b, v71
	v_exp_f32_e32 v160, v160
	v_exp_f32_e32 v161, v161
	v_exp_f32_e32 v162, v162
	v_exp_f32_e32 v163, v163
	v_exp_f32_e32 v164, v164
	v_exp_f32_e32 v165, v165
	v_exp_f32_e32 v166, v166
	v_exp_f32_e32 v167, v167
	v_add_f32_e32 v160, 1.0, v160
	v_add_f32_e32 v161, 1.0, v161
	v_add_f32_e32 v162, 1.0, v162
	v_add_f32_e32 v163, 1.0, v163
	v_add_f32_e32 v164, 1.0, v164
	v_add_f32_e32 v165, 1.0, v165
	v_add_f32_e32 v166, 1.0, v166
	v_add_f32_e32 v167, 1.0, v167
	v_rcp_f32_e32 v160, v160
	v_rcp_f32_e32 v161, v161
	v_rcp_f32_e32 v162, v162
	v_rcp_f32_e32 v163, v163
	v_rcp_f32_e32 v164, v164
	v_rcp_f32_e32 v165, v165
	v_rcp_f32_e32 v166, v166
	v_rcp_f32_e32 v167, v167
	v_pk_mul_f32 v[160:161], v[76:77], v[160:161]
	v_pk_mul_f32 v[162:163], v[78:79], v[162:163]
	v_pk_mul_f32 v[164:165], v[68:69], v[164:165]
	v_pk_mul_f32 v[166:167], v[70:71], v[166:167]
	v_pk_mul_f32 v[72:73], v[160:161], v[72:73]
	v_pk_mul_f32 v[74:75], v[162:163], v[74:75]
	v_pk_mul_f32 v[68:69], v[164:165], v[64:65]
	v_mul_f32_e32 v70, v166, v66
	v_mul_f32_e32 v67, v167, v67
	v_cvt_pk_bf16_f32 v65, v74, v75
	v_cvt_pk_bf16_f32 v66, v68, v69
	v_or_b32_e32 v71, 48, v142
	v_mad_i64_i32 v[68:69], s[26:27], v71, s4, v[112:113]
	v_lshl_add_u64 v[68:69], v[68:69], 0, v[114:115]
	v_cvt_pk_bf16_f32 v64, v72, v73
	v_cvt_pk_bf16_f32 v67, v70, v67
	global_store_dwordx4 v[68:69], v[64:67], off
	s_cmp_lg_u32 s100, 0
	s_cbranch_scc1 .Luph_nost
	s_nop 1
	v_mul_f32_e32 v160, 0xbfb8aa3b, v60
	v_mul_f32_e32 v161, 0xbfb8aa3b, v61
	v_mul_f32_e32 v162, 0xbfb8aa3b, v62
	v_mul_f32_e32 v163, 0xbfb8aa3b, v63
	v_mul_f32_e32 v164, 0xbfb8aa3b, v52
	v_mul_f32_e32 v165, 0xbfb8aa3b, v53
	v_mul_f32_e32 v166, 0xbfb8aa3b, v54
	v_mul_f32_e32 v167, 0xbfb8aa3b, v55
	v_exp_f32_e32 v160, v160
	v_exp_f32_e32 v161, v161
	v_exp_f32_e32 v162, v162
	v_exp_f32_e32 v163, v163
	v_exp_f32_e32 v164, v164
	v_exp_f32_e32 v165, v165
	v_exp_f32_e32 v166, v166
	v_exp_f32_e32 v167, v167
	v_add_f32_e32 v160, 1.0, v160
	v_add_f32_e32 v161, 1.0, v161
	v_add_f32_e32 v162, 1.0, v162
	v_add_f32_e32 v163, 1.0, v163
	v_add_f32_e32 v164, 1.0, v164
	v_add_f32_e32 v165, 1.0, v165
	v_add_f32_e32 v166, 1.0, v166
	v_add_f32_e32 v167, 1.0, v167
	v_rcp_f32_e32 v160, v160
	v_rcp_f32_e32 v161, v161
	v_rcp_f32_e32 v162, v162
	v_rcp_f32_e32 v163, v163
	v_rcp_f32_e32 v164, v164
	v_rcp_f32_e32 v165, v165
	v_rcp_f32_e32 v166, v166
	v_rcp_f32_e32 v167, v167
	v_pk_mul_f32 v[160:161], v[60:61], v[160:161]
	v_pk_mul_f32 v[162:163], v[62:63], v[162:163]
	v_pk_mul_f32 v[164:165], v[52:53], v[164:165]
	v_pk_mul_f32 v[166:167], v[54:55], v[166:167]
	v_pk_mul_f32 v[56:57], v[160:161], v[56:57]
	v_pk_mul_f32 v[58:59], v[162:163], v[58:59]
	v_pk_mul_f32 v[52:53], v[164:165], v[48:49]
	v_mul_f32_e32 v54, v166, v50
	v_mul_f32_e32 v51, v167, v51
	v_add_u32_e32 v64, 0x80, v142
	v_cvt_pk_bf16_f32 v49, v58, v59
	v_cvt_pk_bf16_f32 v50, v52, v53
	v_mad_i64_i32 v[52:53], s[26:27], v64, s4, v[112:113]
	v_lshl_add_u64 v[52:53], v[52:53], 0, v[114:115]
	v_cvt_pk_bf16_f32 v48, v56, v57
	v_cvt_pk_bf16_f32 v51, v54, v51
	global_store_dwordx4 v[52:53], v[48:51], off
	s_nop 1
	v_mul_f32_e32 v160, 0xbfb8aa3b, v44
	v_mul_f32_e32 v161, 0xbfb8aa3b, v45
	v_mul_f32_e32 v162, 0xbfb8aa3b, v46
	v_mul_f32_e32 v163, 0xbfb8aa3b, v47
	v_mul_f32_e32 v164, 0xbfb8aa3b, v36
	v_mul_f32_e32 v165, 0xbfb8aa3b, v37
	v_mul_f32_e32 v166, 0xbfb8aa3b, v38
	v_mul_f32_e32 v167, 0xbfb8aa3b, v39
	v_exp_f32_e32 v160, v160
	v_exp_f32_e32 v161, v161
	v_exp_f32_e32 v162, v162
	v_exp_f32_e32 v163, v163
	v_exp_f32_e32 v164, v164
	v_exp_f32_e32 v165, v165
	v_exp_f32_e32 v166, v166
	v_exp_f32_e32 v167, v167
	v_add_f32_e32 v160, 1.0, v160
	v_add_f32_e32 v161, 1.0, v161
	v_add_f32_e32 v162, 1.0, v162
	v_add_f32_e32 v163, 1.0, v163
	v_add_f32_e32 v164, 1.0, v164
	v_add_f32_e32 v165, 1.0, v165
	v_add_f32_e32 v166, 1.0, v166
	v_add_f32_e32 v167, 1.0, v167
	v_rcp_f32_e32 v160, v160
	v_rcp_f32_e32 v161, v161
	v_rcp_f32_e32 v162, v162
	v_rcp_f32_e32 v163, v163
	v_rcp_f32_e32 v164, v164
	v_rcp_f32_e32 v165, v165
	v_rcp_f32_e32 v166, v166
	v_rcp_f32_e32 v167, v167
	v_pk_mul_f32 v[160:161], v[44:45], v[160:161]
	v_pk_mul_f32 v[162:163], v[46:47], v[162:163]
	v_pk_mul_f32 v[164:165], v[36:37], v[164:165]
	v_pk_mul_f32 v[166:167], v[38:39], v[166:167]
	v_pk_mul_f32 v[40:41], v[160:161], v[40:41]
	v_pk_mul_f32 v[42:43], v[162:163], v[42:43]
	v_pk_mul_f32 v[36:37], v[164:165], v[32:33]
	v_mul_f32_e32 v38, v166, v34
	v_mul_f32_e32 v35, v167, v35
	v_cvt_pk_bf16_f32 v33, v42, v43
	v_cvt_pk_bf16_f32 v34, v36, v37
	v_add_u32_e32 v39, 0x90, v142
	v_mad_i64_i32 v[36:37], s[26:27], v39, s4, v[112:113]
	v_cvt_pk_bf16_f32 v32, v40, v41
	v_lshl_add_u64 v[36:37], v[36:37], 0, v[114:115]
	v_cvt_pk_bf16_f32 v35, v38, v35
	global_store_dwordx4 v[36:37], v[32:35], off
	s_nop 1
	v_mul_f32_e32 v160, 0xbfb8aa3b, v28
	v_mul_f32_e32 v161, 0xbfb8aa3b, v29
	v_mul_f32_e32 v162, 0xbfb8aa3b, v30
	v_mul_f32_e32 v163, 0xbfb8aa3b, v31
	v_mul_f32_e32 v164, 0xbfb8aa3b, v20
	v_mul_f32_e32 v165, 0xbfb8aa3b, v21
	v_mul_f32_e32 v166, 0xbfb8aa3b, v22
	v_mul_f32_e32 v167, 0xbfb8aa3b, v23
	v_exp_f32_e32 v160, v160
	v_exp_f32_e32 v161, v161
	v_exp_f32_e32 v162, v162
	v_exp_f32_e32 v163, v163
	v_exp_f32_e32 v164, v164
	v_exp_f32_e32 v165, v165
	v_exp_f32_e32 v166, v166
	v_exp_f32_e32 v167, v167
	v_add_f32_e32 v160, 1.0, v160
	v_add_f32_e32 v161, 1.0, v161
	v_add_f32_e32 v162, 1.0, v162
	v_add_f32_e32 v163, 1.0, v163
	v_add_f32_e32 v164, 1.0, v164
	v_add_f32_e32 v165, 1.0, v165
	v_add_f32_e32 v166, 1.0, v166
	v_add_f32_e32 v167, 1.0, v167
	v_rcp_f32_e32 v160, v160
	v_rcp_f32_e32 v161, v161
	v_rcp_f32_e32 v162, v162
	v_rcp_f32_e32 v163, v163
	v_rcp_f32_e32 v164, v164
	v_rcp_f32_e32 v165, v165
	v_rcp_f32_e32 v166, v166
	v_rcp_f32_e32 v167, v167
	v_pk_mul_f32 v[160:161], v[28:29], v[160:161]
	v_pk_mul_f32 v[162:163], v[30:31], v[162:163]
	v_pk_mul_f32 v[164:165], v[20:21], v[164:165]
	v_pk_mul_f32 v[166:167], v[22:23], v[166:167]
	v_pk_mul_f32 v[24:25], v[160:161], v[24:25]
	v_pk_mul_f32 v[26:27], v[162:163], v[26:27]
	v_pk_mul_f32 v[20:21], v[164:165], v[16:17]
	v_mul_f32_e32 v22, v166, v18
	v_mul_f32_e32 v19, v167, v19
	v_cvt_pk_bf16_f32 v17, v26, v27
	v_cvt_pk_bf16_f32 v18, v20, v21
	v_add_u32_e32 v23, 0xa0, v142
	v_mad_i64_i32 v[20:21], s[26:27], v23, s4, v[112:113]
	v_cvt_pk_bf16_f32 v16, v24, v25
	v_lshl_add_u64 v[20:21], v[20:21], 0, v[114:115]
	v_cvt_pk_bf16_f32 v19, v22, v19
	global_store_dwordx4 v[20:21], v[16:19], off
	s_nop 1
	v_mul_f32_e32 v160, 0xbfb8aa3b, v12
	v_mul_f32_e32 v161, 0xbfb8aa3b, v13
	v_mul_f32_e32 v162, 0xbfb8aa3b, v14
	v_mul_f32_e32 v163, 0xbfb8aa3b, v15
	v_mul_f32_e32 v164, 0xbfb8aa3b, v4
	v_mul_f32_e32 v165, 0xbfb8aa3b, v5
	v_mul_f32_e32 v166, 0xbfb8aa3b, v6
	v_mul_f32_e32 v167, 0xbfb8aa3b, v7
	v_exp_f32_e32 v160, v160
	v_exp_f32_e32 v161, v161
	v_exp_f32_e32 v162, v162
	v_exp_f32_e32 v163, v163
	v_exp_f32_e32 v164, v164
	v_exp_f32_e32 v165, v165
	v_exp_f32_e32 v166, v166
	v_exp_f32_e32 v167, v167
	v_add_f32_e32 v160, 1.0, v160
	v_add_f32_e32 v161, 1.0, v161
	v_add_f32_e32 v162, 1.0, v162
	v_add_f32_e32 v163, 1.0, v163
	v_add_f32_e32 v164, 1.0, v164
	v_add_f32_e32 v165, 1.0, v165
	v_add_f32_e32 v166, 1.0, v166
	v_add_f32_e32 v167, 1.0, v167
	v_rcp_f32_e32 v160, v160
	v_rcp_f32_e32 v161, v161
	v_rcp_f32_e32 v162, v162
	v_rcp_f32_e32 v163, v163
	v_rcp_f32_e32 v164, v164
	v_rcp_f32_e32 v165, v165
	v_rcp_f32_e32 v166, v166
	v_rcp_f32_e32 v167, v167
	v_pk_mul_f32 v[160:161], v[12:13], v[160:161]
	v_pk_mul_f32 v[162:163], v[14:15], v[162:163]
	v_pk_mul_f32 v[164:165], v[4:5], v[164:165]
	v_pk_mul_f32 v[166:167], v[6:7], v[166:167]
	v_pk_mul_f32 v[8:9], v[160:161], v[8:9]
	v_pk_mul_f32 v[10:11], v[162:163], v[10:11]
	v_pk_mul_f32 v[4:5], v[164:165], v[0:1]
	v_mul_f32_e32 v6, v166, v2
	v_mul_f32_e32 v3, v167, v3
	v_cvt_pk_bf16_f32 v1, v10, v11
	v_cvt_pk_bf16_f32 v2, v4, v5
	v_add_u32_e32 v7, 0xb0, v142
	v_mad_i64_i32 v[4:5], s[26:27], v7, s4, v[112:113]
	v_lshl_add_u64 v[4:5], v[4:5], 0, v[114:115]
	v_cvt_pk_bf16_f32 v0, v8, v9
	v_cvt_pk_bf16_f32 v3, v6, v3
	global_store_dwordx4 v[4:5], v[0:3], off
